# windowed attention (mixer A) hand-written as pair-units on blocks 144..255 (two q-heads per pass, window mask, sink), neighbourhood units dealt as before
# speedup vs baseline: 1.0040x; 1.0040x over previous
.Lwa_entry:
	s_mov_b32 s40, s44
	s_load_dwordx2 s[34:35], s[64:65], 0x68
	s_mov_b64 exec, -1
	s_load_dwordx2 s[4:5], s[64:65], 0xf8
	s_mov_b32 s100, 0x3e38aa3b
	s_mov_b32 s101, 0
	v_mov_b32_e32 v86, 0x3e38aa3b
	v_and_b32_e32 v144, 63, v247
	v_lshrrev_b32_e32 v145, 6, v247
	v_and_b32_e32 v146, 15, v144
	v_lshrrev_b32_e32 v147, 4, v144
	v_readfirstlane_b32 s21, v145
	v_bfe_u32 v148, v146, 1, 3
	v_lshlrev_b32_e32 v149, 7, v146
	v_xor_b32_e32 v150, v147, v148
	v_lshl_add_u32 v136, v150, 4, v149
	v_add_u32_e32 v136, 16, v136
	v_xor_b32_e32 v150, 4, v150
	v_lshl_add_u32 v137, v150, 4, v149
	v_add_u32_e32 v137, 16, v137
	v_lshrrev_b32_e32 v151, 1, v147
	v_and_b32_e32 v152, 1, v147
	v_lshlrev_b32_e32 v152, 3, v152
	v_add_u32_e32 v152, v152, v149
	v_add_u32_e32 v152, 0x2010, v152
	v_add_u32_e32 v153, 0, v151
	v_xor_b32_e32 v153, v153, v148
	v_lshl_add_u32 v138, v153, 4, v152
	v_add_u32_e32 v153, 2, v151
	v_xor_b32_e32 v153, v153, v148
	v_lshl_add_u32 v139, v153, 4, v152
	v_add_u32_e32 v153, 4, v151
	v_xor_b32_e32 v153, v153, v148
	v_lshl_add_u32 v140, v153, 4, v152
	v_add_u32_e32 v153, 6, v151
	v_xor_b32_e32 v153, v153, v148
	v_lshl_add_u32 v141, v153, 4, v152
	s_lshl_b32 s0, s21, 3
	v_lshrrev_b32_e32 v153, 3, v144
	v_add_u32_e32 v153, s0, v153
	v_bfe_u32 v154, v153, 1, 3
	v_and_b32_e32 v155, 7, v144
	v_xor_b32_e32 v154, v154, v155
	v_lshlrev_b32_e32 v154, 4, v154
	v_mul_u32_u24_e32 v142, 0x3000, v153
	v_add_u32_e32 v142, v142, v154
	v_mul_u32_u24_e32 v143, 0x9000, v153
	v_add_u32_e32 v143, v143, v154
	s_lshl_b32 s32, s21, 10
	s_add_u32 s32, s32, 16
	s_add_u32 s41, s32, 0x2000
	s_sub_u32 s1, s40, 144
	s_waitcnt lgkmcnt(0)
.Lwa_unit:
	v_and_b32_e32 v144, 63, v247
	s_and_b32 s80, s1, 15
	s_bfe_u32 s81, s1, 0x10004
	s_lshr_b32 s43, s1, 5
	s_lshl_b32 s33, s80, 7
	s_sub_u32 s33, s33, 128
	s_max_i32 s33, s33, 0
	s_lshl_b32 s0, s80, 7
	s_add_u32 s0, s0, 256
	s_min_u32 s0, s0, 0x800
	s_sub_u32 s0, s0, s33
	s_lshr_b32 s0, s0, 6
	s_add_u32 s45, s0, 4
	v_readlane_b32 s0, v254, 38
	s_lshl_b32 s0, s0, 4
	s_lshl_b32 s92, s81, 3
	s_add_u32 s0, s0, s92
	s_load_dwordx2 s[50:51], s[34:35], s0
	s_lshl_b32 s0, s80, 7
	s_sub_u32 s0, s0, s33
	s_lshl_b32 s92, s21, 4
	s_add_u32 s0, s0, s92
	s_add_u32 s0, s0, 128
	v_and_b32_e32 v145, 15, v144
	v_lshrrev_b32_e32 v146, 4, v144
	v_add_u32_e32 v158, s0, v145
	v_lshlrev_b32_e32 v146, 2, v146
	v_sub_u32_e32 v158, v158, v146
	v_mov_b32_e32 v159, 0xf149f2ca
	s_lshl_b32 s0, s81, 7
	s_add_u32 s0, s0, 0x200
	s_add_u32 s6, s4, 0x9f00000
	s_addc_u32 s7, s5, 0
	s_add_u32 s6, s6, s0
	s_addc_u32 s7, s7, 0
	s_mul_i32 s0, s43, 0x1800000
	s_add_u32 s96, s6, s0
	s_addc_u32 s97, s7, 0
	s_mul_i32 s0, s33, 0x3000
	s_add_u32 s96, s96, s0
	s_addc_u32 s97, s97, 0
	s_mul_i32 s0, s43, 0x300000
	s_add_u32 s6, s6, s0
	s_addc_u32 s7, s7, 0
	s_add_u32 s6, s6, 0xc000000
	s_addc_u32 s7, s7, 0
	s_lshl_b32 s0, s81, 6
	s_mul_i32 s0, s0, 0x9000
	s_add_u32 s8, s4, 0x17700000
	s_addc_u32 s9, s5, 0
	s_add_u32 s8, s8, s0
	s_addc_u32 s9, s9, 0
	s_lshl_b32 s0, s43, 12
	s_add_u32 s98, s8, s0
	s_addc_u32 s99, s9, 0
	s_lshl_b32 s0, s33, 1
	s_add_u32 s98, s98, s0
	s_addc_u32 s99, s99, 0
	s_lshl_b32 s0, s43, 9
	s_add_u32 s0, s0, 0x8000
	s_add_u32 s8, s8, s0
	s_addc_u32 s9, s9, 0
	s_lshl_b32 s0, s43, 11
	s_lshl_b32 s92, s80, 7
	s_add_u32 s0, s0, s92
	s_lshl_b32 s92, s21, 4
	s_add_u32 s0, s0, s92
	v_and_b32_e32 v146, 15, v144
	v_add_u32_e32 v146, s0, v146
	v_lshrrev_b32_e32 v147, 4, v144
	s_lshl_b32 s92, s81, 8
	v_lshl_add_u32 v148, v147, 4, s92
	v_mov_b32_e32 v149, 0
	s_movk_i32 s93, 0x3000
	v_mad_u64_u32 v[82:83], s[90:91], v146, s93, v[148:149]
	s_add_u32 s90, s4, 0x9f00000
	s_addc_u32 s91, s5, 0
	v_lshl_add_u64 v[82:83], v[82:83], 0, s[90:91]
	global_load_dwordx4 v[2:5], v[82:83], off
	global_load_dwordx4 v[6:9], v[82:83], off offset:64
	global_load_dwordx4 v[10:13], v[82:83], off offset:128
	global_load_dwordx4 v[14:17], v[82:83], off offset:192
	s_lshl_b32 s92, s81, 8
	v_lshl_add_u32 v148, v147, 3, s92
	v_lshlrev_b32_e32 v150, 11, v146
	v_add_u32_e32 v148, v148, v150
	s_add_u32 s90, s4, 0x1e300000
	s_addc_u32 s91, s5, 0
	v_lshl_add_u64 v[84:85], s[90:91], 0, v[148:149]
	v_mov_b32_e32 v100, 0
	v_mov_b32_e32 v101, 0
	v_mov_b32_e32 v102, 0
	v_mov_b32_e32 v103, 0
	v_mov_b32_e32 v104, 0
	v_mov_b32_e32 v105, 0
	v_mov_b32_e32 v106, 0
	v_mov_b32_e32 v107, 0
	v_mov_b32_e32 v108, 0
	v_mov_b32_e32 v109, 0
	v_mov_b32_e32 v110, 0
	v_mov_b32_e32 v111, 0
	v_mov_b32_e32 v112, 0
	v_mov_b32_e32 v113, 0
	v_mov_b32_e32 v114, 0
	v_mov_b32_e32 v115, 0
	v_mov_b32_e32 v116, 0
	v_mov_b32_e32 v117, 0
	v_mov_b32_e32 v118, 0
	v_mov_b32_e32 v119, 0
	v_mov_b32_e32 v120, 0
	v_mov_b32_e32 v121, 0
	v_mov_b32_e32 v122, 0
	v_mov_b32_e32 v123, 0
	v_mov_b32_e32 v124, 0
	v_mov_b32_e32 v125, 0
	v_mov_b32_e32 v126, 0
	v_mov_b32_e32 v127, 0
	v_mov_b32_e32 v128, 0
	v_mov_b32_e32 v129, 0
	v_mov_b32_e32 v130, 0
	v_mov_b32_e32 v131, 0
	v_mov_b32_e32 v132, 0xf149f2ca
	v_mov_b32_e32 v133, 0xf149f2ca
	v_mov_b32_e32 v134, 0
	v_mov_b32_e32 v135, 0
	s_mov_b32 s89, 0
	s_mov_b32 s42, s45
	s_mov_b32 s90, 0
	s_barrier
	s_cmp_eq_u32 s89, 4
	s_cbranch_scc0 .Lwa_nosw1
	s_mov_b64 s[6:7], s[96:97]
	s_mov_b64 s[8:9], s[98:99]

.Lwa_cmp0:
	s_bitcmp1_b32 s101, 0
	s_cbranch_scc1 .Lwa_idle0
	s_nop 3
	s_cmp_lt_u32 s90, 4
	s_cbranch_scc1 .Lwa_nomask0
	v_subrev_u32_e32 v160, 0, v158
	v_cmp_gt_u32_e32 vcc, 0x101, v160
	v_cndmask_b32_e32 v50, v159, v50, vcc
	v_cndmask_b32_e32 v66, v159, v66, vcc
	v_subrev_u32_e32 v160, 1, v158
	v_cmp_gt_u32_e32 vcc, 0x101, v160
	v_cndmask_b32_e32 v51, v159, v51, vcc
	v_cndmask_b32_e32 v67, v159, v67, vcc
	v_subrev_u32_e32 v160, 2, v158
	v_cmp_gt_u32_e32 vcc, 0x101, v160
	v_cndmask_b32_e32 v52, v159, v52, vcc
	v_cndmask_b32_e32 v68, v159, v68, vcc
	v_subrev_u32_e32 v160, 3, v158
	v_cmp_gt_u32_e32 vcc, 0x101, v160
	v_cndmask_b32_e32 v53, v159, v53, vcc
	v_cndmask_b32_e32 v69, v159, v69, vcc
	v_subrev_u32_e32 v160, 16, v158
	v_cmp_gt_u32_e32 vcc, 0x101, v160
	v_cndmask_b32_e32 v54, v159, v54, vcc
	v_cndmask_b32_e32 v70, v159, v70, vcc
	v_subrev_u32_e32 v160, 17, v158
	v_cmp_gt_u32_e32 vcc, 0x101, v160
	v_cndmask_b32_e32 v55, v159, v55, vcc
	v_cndmask_b32_e32 v71, v159, v71, vcc
	v_subrev_u32_e32 v160, 18, v158
	v_cmp_gt_u32_e32 vcc, 0x101, v160
	v_cndmask_b32_e32 v56, v159, v56, vcc
	v_cndmask_b32_e32 v72, v159, v72, vcc
	v_subrev_u32_e32 v160, 19, v158
	v_cmp_gt_u32_e32 vcc, 0x101, v160
	v_cndmask_b32_e32 v57, v159, v57, vcc
	v_cndmask_b32_e32 v73, v159, v73, vcc
	v_subrev_u32_e32 v160, 32, v158
	v_cmp_gt_u32_e32 vcc, 0x101, v160
	v_cndmask_b32_e32 v58, v159, v58, vcc
	v_cndmask_b32_e32 v74, v159, v74, vcc
	v_subrev_u32_e32 v160, 33, v158
	v_cmp_gt_u32_e32 vcc, 0x101, v160
	v_cndmask_b32_e32 v59, v159, v59, vcc
	v_cndmask_b32_e32 v75, v159, v75, vcc
	v_subrev_u32_e32 v160, 34, v158
	v_cmp_gt_u32_e32 vcc, 0x101, v160
	v_cndmask_b32_e32 v60, v159, v60, vcc
	v_cndmask_b32_e32 v76, v159, v76, vcc
	v_subrev_u32_e32 v160, 35, v158
	v_cmp_gt_u32_e32 vcc, 0x101, v160
	v_cndmask_b32_e32 v61, v159, v61, vcc
	v_cndmask_b32_e32 v77, v159, v77, vcc
	v_subrev_u32_e32 v160, 48, v158
	v_cmp_gt_u32_e32 vcc, 0x101, v160
	v_cndmask_b32_e32 v62, v159, v62, vcc
	v_cndmask_b32_e32 v78, v159, v78, vcc
	v_subrev_u32_e32 v160, 49, v158
	v_cmp_gt_u32_e32 vcc, 0x101, v160
	v_cndmask_b32_e32 v63, v159, v63, vcc
	v_cndmask_b32_e32 v79, v159, v79, vcc
	v_subrev_u32_e32 v160, 50, v158
	v_cmp_gt_u32_e32 vcc, 0x101, v160
	v_cndmask_b32_e32 v64, v159, v64, vcc
	v_cndmask_b32_e32 v80, v159, v80, vcc
	v_subrev_u32_e32 v160, 51, v158
	v_cmp_gt_u32_e32 vcc, 0x101, v160
	v_cndmask_b32_e32 v65, v159, v65, vcc
	v_cndmask_b32_e32 v81, v159, v81, vcc
	v_subrev_u32_e32 v158, 64, v158
.Lwa_nomask0:
	v_max3_f32 v144, v50, v51, v52
	v_max3_f32 v145, v53, v54, v55
	v_max3_f32 v150, v56, v57, v58
	v_max3_f32 v151, v59, v60, v61
	v_max3_f32 v152, v62, v63, v64
	v_max3_f32 v144, v144, v145, v65
	v_max3_f32 v144, v144, v150, v151
	v_max_f32_e32 v144, v144, v152
	v_mov_b32_e32 v145, v144
	s_nop 1
	v_permlane16_swap_b32_e32 v144, v145
	v_max_f32_e32 v144, v144, v145
	v_mov_b32_e32 v145, v144
	s_nop 1
	v_permlane32_swap_b32_e32 v144, v145
	v_max_f32_e32 v144, v144, v145
	v_mul_f32_e32 v144, s100, v144
	v_max_f32_e32 v146, v132, v144
	v_cmp_gt_f32_e32 vcc, v146, v132
	s_cbranch_vccz .Lwa_nors1
	v_sub_f32_e32 v148, v132, v146
	v_exp_f32_e32 v148, v148
	v_mov_b32_e32 v132, v146
	s_nop 0
	v_mul_f32_e32 v134, v134, v148
	v_pk_mul_f32 v[100:101], v[100:101], v[148:149] op_sel_hi:[1,0]
	v_pk_mul_f32 v[102:103], v[102:103], v[148:149] op_sel_hi:[1,0]
	v_pk_mul_f32 v[104:105], v[104:105], v[148:149] op_sel_hi:[1,0]
	v_pk_mul_f32 v[106:107], v[106:107], v[148:149] op_sel_hi:[1,0]
	v_pk_mul_f32 v[108:109], v[108:109], v[148:149] op_sel_hi:[1,0]
	v_pk_mul_f32 v[110:111], v[110:111], v[148:149] op_sel_hi:[1,0]
	v_pk_mul_f32 v[112:113], v[112:113], v[148:149] op_sel_hi:[1,0]
	v_pk_mul_f32 v[114:115], v[114:115], v[148:149] op_sel_hi:[1,0]

.Lwa_idle0:
	s_add_u32 s90, s90, 1
	s_sub_u32 s42, s42, 1
	s_cmp_eq_u32 s42, 0
	s_cbranch_scc1 .Lwa_fin
	s_bitcmp1_b32 s101, 0
	s_cbranch_scc1 .Lwa_sync1
	s_waitcnt lgkmcnt(0)
	v_mfma_f32_16x16x32_bf16 v[50:53], v[18:21], v[2:5], 0
	v_mfma_f32_16x16x32_bf16 v[54:57], v[26:29], v[2:5], 0
	v_mfma_f32_16x16x32_bf16 v[58:61], v[34:37], v[2:5], 0
	v_mfma_f32_16x16x32_bf16 v[62:65], v[42:45], v[2:5], 0
	v_mfma_f32_16x16x32_bf16 v[50:53], v[22:25], v[6:9], v[50:53]
	v_mfma_f32_16x16x32_bf16 v[54:57], v[30:33], v[6:9], v[54:57]
	v_mfma_f32_16x16x32_bf16 v[58:61], v[38:41], v[6:9], v[58:61]
	v_mfma_f32_16x16x32_bf16 v[62:65], v[46:49], v[6:9], v[62:65]
	ds_read_b64 v[168:169], v138 offset:16384
	ds_read_b64 v[170:171], v139 offset:16384
	ds_read_b64 v[172:173], v140 offset:16384
	ds_read_b64 v[174:175], v141 offset:16384
	ds_read_b64 v[176:177], v138 offset:18432
	ds_read_b64 v[178:179], v139 offset:18432
	ds_read_b64 v[180:181], v140 offset:18432
	ds_read_b64 v[182:183], v141 offset:18432
	v_mfma_f32_16x16x32_bf16 v[66:69], v[18:21], v[10:13], 0
	v_mfma_f32_16x16x32_bf16 v[70:73], v[26:29], v[10:13], 0
	v_mfma_f32_16x16x32_bf16 v[74:77], v[34:37], v[10:13], 0
	v_mfma_f32_16x16x32_bf16 v[78:81], v[42:45], v[10:13], 0
	v_mfma_f32_16x16x32_bf16 v[66:69], v[22:25], v[14:17], v[66:69]
	v_mfma_f32_16x16x32_bf16 v[70:73], v[30:33], v[14:17], v[70:73]
	v_mfma_f32_16x16x32_bf16 v[74:77], v[38:41], v[14:17], v[74:77]
	v_mfma_f32_16x16x32_bf16 v[78:81], v[46:49], v[14:17], v[78:81]
	ds_read_b64 v[184:185], v138 offset:20480
	ds_read_b64 v[186:187], v139 offset:20480
	ds_read_b64 v[188:189], v140 offset:20480
	ds_read_b64 v[190:191], v141 offset:20480
	ds_read_b64 v[192:193], v138 offset:22528
	ds_read_b64 v[194:195], v139 offset:22528
	ds_read_b64 v[196:197], v140 offset:22528
	ds_read_b64 v[198:199], v141 offset:22528
	s_waitcnt lgkmcnt(0)

.Lwa_idle1:
	s_add_u32 s90, s90, 1
	s_sub_u32 s42, s42, 1
	s_cmp_eq_u32 s42, 0
	s_cbranch_scc1 .Lwa_fin
	s_bitcmp1_b32 s101, 0
	s_cbranch_scc1 .Lwa_sync2
	s_waitcnt lgkmcnt(0)
	v_mfma_f32_16x16x32_bf16 v[50:53], v[18:21], v[2:5], 0
	v_mfma_f32_16x16x32_bf16 v[54:57], v[26:29], v[2:5], 0
	v_mfma_f32_16x16x32_bf16 v[58:61], v[34:37], v[2:5], 0
	v_mfma_f32_16x16x32_bf16 v[62:65], v[42:45], v[2:5], 0
	v_mfma_f32_16x16x32_bf16 v[50:53], v[22:25], v[6:9], v[50:53]
	v_mfma_f32_16x16x32_bf16 v[54:57], v[30:33], v[6:9], v[54:57]
	v_mfma_f32_16x16x32_bf16 v[58:61], v[38:41], v[6:9], v[58:61]
	v_mfma_f32_16x16x32_bf16 v[62:65], v[46:49], v[6:9], v[62:65]
	ds_read_b64 v[168:169], v138 offset:32768
	ds_read_b64 v[170:171], v139 offset:32768
	ds_read_b64 v[172:173], v140 offset:32768
	ds_read_b64 v[174:175], v141 offset:32768
	ds_read_b64 v[176:177], v138 offset:34816
	ds_read_b64 v[178:179], v139 offset:34816
	ds_read_b64 v[180:181], v140 offset:34816
	ds_read_b64 v[182:183], v141 offset:34816
	v_mfma_f32_16x16x32_bf16 v[66:69], v[18:21], v[10:13], 0
	v_mfma_f32_16x16x32_bf16 v[70:73], v[26:29], v[10:13], 0
	v_mfma_f32_16x16x32_bf16 v[74:77], v[34:37], v[10:13], 0
	v_mfma_f32_16x16x32_bf16 v[78:81], v[42:45], v[10:13], 0
	v_mfma_f32_16x16x32_bf16 v[66:69], v[22:25], v[14:17], v[66:69]
	v_mfma_f32_16x16x32_bf16 v[70:73], v[30:33], v[14:17], v[70:73]
	v_mfma_f32_16x16x32_bf16 v[74:77], v[38:41], v[14:17], v[74:77]
	v_mfma_f32_16x16x32_bf16 v[78:81], v[46:49], v[14:17], v[78:81]
	ds_read_b64 v[184:185], v138 offset:36864
	ds_read_b64 v[186:187], v139 offset:36864
	ds_read_b64 v[188:189], v140 offset:36864
	ds_read_b64 v[190:191], v141 offset:36864
	ds_read_b64 v[192:193], v138 offset:38912
	ds_read_b64 v[194:195], v139 offset:38912
	ds_read_b64 v[196:197], v140 offset:38912
	ds_read_b64 v[198:199], v141 offset:38912
	s_waitcnt lgkmcnt(0)

.Lwa_idle2:
	s_add_u32 s90, s90, 1
	s_sub_u32 s42, s42, 1
	s_cmp_eq_u32 s42, 0
	s_cbranch_scc1 .Lwa_fin
	s_bitcmp1_b32 s101, 0
	s_cbranch_scc1 .Lwa_sync3
	s_waitcnt lgkmcnt(0)
	v_mfma_f32_16x16x32_bf16 v[50:53], v[18:21], v[2:5], 0
	v_mfma_f32_16x16x32_bf16 v[54:57], v[26:29], v[2:5], 0
	v_mfma_f32_16x16x32_bf16 v[58:61], v[34:37], v[2:5], 0
	v_mfma_f32_16x16x32_bf16 v[62:65], v[42:45], v[2:5], 0
	v_mfma_f32_16x16x32_bf16 v[50:53], v[22:25], v[6:9], v[50:53]
	v_mfma_f32_16x16x32_bf16 v[54:57], v[30:33], v[6:9], v[54:57]
	v_mfma_f32_16x16x32_bf16 v[58:61], v[38:41], v[6:9], v[58:61]
	v_mfma_f32_16x16x32_bf16 v[62:65], v[46:49], v[6:9], v[62:65]
	ds_read_b64 v[168:169], v138 offset:49152
	ds_read_b64 v[170:171], v139 offset:49152
	ds_read_b64 v[172:173], v140 offset:49152
	ds_read_b64 v[174:175], v141 offset:49152
	ds_read_b64 v[176:177], v138 offset:51200
	ds_read_b64 v[178:179], v139 offset:51200
	ds_read_b64 v[180:181], v140 offset:51200
	ds_read_b64 v[182:183], v141 offset:51200
	v_mfma_f32_16x16x32_bf16 v[66:69], v[18:21], v[10:13], 0
	v_mfma_f32_16x16x32_bf16 v[70:73], v[26:29], v[10:13], 0
	v_mfma_f32_16x16x32_bf16 v[74:77], v[34:37], v[10:13], 0
	v_mfma_f32_16x16x32_bf16 v[78:81], v[42:45], v[10:13], 0
	v_mfma_f32_16x16x32_bf16 v[66:69], v[22:25], v[14:17], v[66:69]
	v_mfma_f32_16x16x32_bf16 v[70:73], v[30:33], v[14:17], v[70:73]
	v_mfma_f32_16x16x32_bf16 v[74:77], v[38:41], v[14:17], v[74:77]
	v_mfma_f32_16x16x32_bf16 v[78:81], v[46:49], v[14:17], v[78:81]
	ds_read_b64 v[184:185], v138 offset:53248
	ds_read_b64 v[186:187], v139 offset:53248
	ds_read_b64 v[188:189], v140 offset:53248
	ds_read_b64 v[190:191], v141 offset:53248
	ds_read_b64 v[192:193], v138 offset:55296
	ds_read_b64 v[194:195], v139 offset:55296
	ds_read_b64 v[196:197], v140 offset:55296
	ds_read_b64 v[198:199], v141 offset:55296
	s_waitcnt lgkmcnt(0)

.Lwa_idle3:
	s_add_u32 s90, s90, 1
	s_sub_u32 s42, s42, 1
	s_cmp_eq_u32 s42, 0
	s_cbranch_scc1 .Lwa_fin
	s_cmp_eq_u32 s42, 0
	s_cbranch_scc0 .Lwa_loop
.Lwa_fin:
	s_waitcnt lgkmcnt(0)
	s_bitcmp1_b32 s101, 0
	s_cbranch_scc1 .Lwa_nostore
	s_nop 7
	s_nop 1
	v_mov_b32_e32 v145, v134
	s_nop 1
	v_permlane16_swap_b32_e32 v134, v145
	v_add_f32_e32 v134, v134, v145
	v_mov_b32_e32 v145, v134
	s_nop 1
	v_permlane32_swap_b32_e32 v134, v145
	v_add_f32_e32 v134, v134, v145
	v_mov_b32_e32 v145, s50
	v_mul_f32_e32 v145, 0x3fb8aa3b, v145
	v_sub_f32_e32 v145, v145, v132
	v_exp_f32_e32 v145, v145
	s_nop 0
	v_add_f32_e32 v134, v134, v145
	v_rcp_f32_e32 v134, v134
	s_nop 0
	v_mul_f32_e32 v100, v100, v134
	v_mul_f32_e32 v101, v101, v134
	v_mul_f32_e32 v102, v102, v134
	v_mul_f32_e32 v103, v103, v134
	v_mul_f32_e32 v104, v104, v134
	v_mul_f32_e32 v105, v105, v134
	v_mul_f32_e32 v106, v106, v134
	v_mul_f32_e32 v107, v107, v134
	v_mul_f32_e32 v108, v108, v134
	v_mul_f32_e32 v109, v109, v134
	v_mul_f32_e32 v110, v110, v134
	v_mul_f32_e32 v111, v111, v134
	v_mul_f32_e32 v112, v112, v134
	v_mul_f32_e32 v113, v113, v134
	v_mul_f32_e32 v114, v114, v134
	v_mul_f32_e32 v115, v115, v134
	v_cvt_pk_bf16_f32 v146, v100, v101
	v_cvt_pk_bf16_f32 v147, v102, v103
	v_cvt_pk_bf16_f32 v148, v104, v105
	v_cvt_pk_bf16_f32 v149, v106, v107
	v_cvt_pk_bf16_f32 v150, v108, v109
	v_cvt_pk_bf16_f32 v151, v110, v111
	v_cvt_pk_bf16_f32 v152, v112, v113
	v_cvt_pk_bf16_f32 v153, v114, v115
	global_store_dwordx2 v[84:85], v[146:147], off offset:0
	global_store_dwordx2 v[84:85], v[148:149], off offset:32
	global_store_dwordx2 v[84:85], v[150:151], off offset:64
	global_store_dwordx2 v[84:85], v[152:153], off offset:96
	v_mov_b32_e32 v145, v135
	s_nop 1
	v_permlane16_swap_b32_e32 v135, v145
	v_add_f32_e32 v135, v135, v145
	v_mov_b32_e32 v145, v135
	s_nop 1
	v_permlane32_swap_b32_e32 v135, v145
	v_add_f32_e32 v135, v135, v145
	v_mov_b32_e32 v145, s51
	v_mul_f32_e32 v145, 0x3fb8aa3b, v145
	v_sub_f32_e32 v145, v145, v133
	v_exp_f32_e32 v145, v145
	s_nop 0
	v_add_f32_e32 v135, v135, v145
	v_rcp_f32_e32 v135, v135
	s_nop 0
	v_mul_f32_e32 v116, v116, v135
	v_mul_f32_e32 v117, v117, v135
	v_mul_f32_e32 v118, v118, v135
	v_mul_f32_e32 v119, v119, v135
	v_mul_f32_e32 v120, v120, v135
	v_mul_f32_e32 v121, v121, v135
	v_mul_f32_e32 v122, v122, v135
	v_mul_f32_e32 v123, v123, v135
	v_mul_f32_e32 v124, v124, v135
	v_mul_f32_e32 v125, v125, v135
	v_mul_f32_e32 v126, v126, v135
	v_mul_f32_e32 v127, v127, v135
	v_mul_f32_e32 v128, v128, v135
	v_mul_f32_e32 v129, v129, v135
	v_mul_f32_e32 v130, v130, v135
	v_mul_f32_e32 v131, v131, v135
	v_cvt_pk_bf16_f32 v146, v116, v117
	v_cvt_pk_bf16_f32 v147, v118, v119
	v_cvt_pk_bf16_f32 v148, v120, v121
	v_cvt_pk_bf16_f32 v149, v122, v123
	v_cvt_pk_bf16_f32 v150, v124, v125
	v_cvt_pk_bf16_f32 v151, v126, v127
	v_cvt_pk_bf16_f32 v152, v128, v129
	v_cvt_pk_bf16_f32 v153, v130, v131
	global_store_dwordx2 v[84:85], v[146:147], off offset:128
	global_store_dwordx2 v[84:85], v[148:149], off offset:160
	global_store_dwordx2 v[84:85], v[150:151], off offset:192
	global_store_dwordx2 v[84:85], v[152:153], off offset:224
.Lwa_nostore:
	s_bitcmp1_b32 s101, 1
	s_cbranch_scc1 .Lwa_done
	s_add_u32 s1, s1, 0x70
	s_cmpk_lt_u32 s1, 0xe0
	s_cbranch_scc1 .Lwa_unit
	s_sub_u32 s0, s40, 192
	s_cmp_lt_u32 s0, 64
	s_cbranch_scc0 .Lwa_done
	s_lshr_b32 s1, s0, 1
	s_add_u32 s1, s1, 0xe0
	s_and_b32 s0, s0, 1
	s_lshr_b32 s92, s21, 2
	s_cmp_lg_u32 s92, s0
	s_cselect_b32 s101, 3, 2
	s_branch .Lwa_unit
.Lwa_done:
	s_barrier
	s_sub_u32 s4, s40, 144
	s_add_u32 s4, s4, 0x200
	s_movk_i32 s0, 0x2a0
	s_movk_i32 s1, 0x70
	s_branch .LBB0_627
.LBB0_626:
	s_branch .Lwa_entry
	s_movk_i32 s4, 0xff70
	s_movk_i32 s0, 0x2a0
	s_movk_i32 s1, 0x70
	s_add_i32 s4, s44, s4
	s_cmp_ge_i32 s4, s0
	s_cbranch_scc1 .LBB0_727
